# phase 0 weight conversion: the four predicated tile loads per 64x64 tile issued together into separate registers (one wait) instead of load-wait-ds_write four times
# speedup vs baseline: 1.0108x; 1.0108x over previous
.LBB0_43:
	s_or_b64 exec, exec, s[0:1]
	s_waitcnt vmcnt(0)
	ds_write2_b32 v16, v100, v101 offset1:1
	ds_write2_b32 v16, v102, v103 offset0:2 offset1:3
	ds_write2_b32 v18, v104, v105 offset1:1
	ds_write2_b32 v19, v106, v107 offset1:1
	ds_write2_b32 v20, v108, v109 offset1:1
	ds_write2_b32 v21, v110, v111 offset1:1
	ds_write2_b32 v23, v112, v113 offset1:1
	ds_write2_b32 v24, v114, v115 offset1:1
	s_waitcnt lgkmcnt(0)
	s_barrier
	ds_read2_b32 v[6:7], v14 offset1:32
	ds_read2_b32 v[26:27], v14 offset0:65 offset1:97
	ds_read2_b32 v[28:29], v14 offset0:130 offset1:162
	ds_read2_b32 v[30:31], v14 offset0:195 offset1:227
	ds_read2_b32 v[32:33], v25 offset0:4 offset1:36
	ds_read2_b32 v[34:35], v25 offset0:69 offset1:101
	ds_read2_b32 v[36:37], v25 offset0:134 offset1:166
	ds_read2_b32 v[38:39], v25 offset0:199 offset1:231
	s_lshl_b32 s0, s23, 10
	s_sub_i32 s0, s20, s0
	v_add_u32_e32 v42, s22, v13
	s_ashr_i32 s1, s0, 31
	v_ashrrev_i32_e32 v43, 31, v42
	v_lshl_add_u64 v[40:41], s[0:1], 1, v[10:11]
	v_lshlrev_b64 v[44:45], 11, v[42:43]
	s_waitcnt lgkmcnt(6)
	v_cvt_pk_bf16_f32 v2, v6, v26
	s_waitcnt lgkmcnt(4)
	v_cvt_pk_bf16_f32 v3, v28, v30
	s_waitcnt lgkmcnt(2)
	v_cvt_pk_bf16_f32 v4, v32, v34
	s_waitcnt lgkmcnt(0)
	v_cvt_pk_bf16_f32 v5, v36, v38
	v_lshl_add_u64 v[44:45], v[40:41], 0, v[44:45]
	v_add_u32_e32 v6, 32, v42
	global_store_dwordx4 v[44:45], v[2:5], off sc1
	s_add_i32 s9, s9, s33
	s_add_i32 s20, s20, s21
	v_cvt_pk_bf16_f32 v2, v7, v27
	v_ashrrev_i32_e32 v7, 31, v6
	v_lshlrev_b64 v[6:7], 11, v[6:7]
	v_cvt_pk_bf16_f32 v3, v29, v31
	v_cvt_pk_bf16_f32 v4, v33, v35
	v_cvt_pk_bf16_f32 v5, v37, v39
	v_lshl_add_u64 v[6:7], v[40:41], 0, v[6:7]
	s_cmpk_lt_i32 s9, 0xc0
	v_add_u32_e32 v15, s11, v15
	global_store_dwordx4 v[6:7], v[2:5], off sc1
	s_barrier
	s_cbranch_scc0 .LBB0_52
.LBB0_44:
	s_ashr_i32 s0, s9, 31
	s_lshr_b32 s0, s0, 28
	s_add_i32 s0, s9, s0
	s_ashr_i32 s23, s0, 4
	s_lshl_b32 s22, s23, 6
	v_or_b32_e32 v2, s22, v12
	s_mul_i32 s0, s23, 0xfff50040
	v_add_u32_e32 v26, s0, v15
	v_cmp_gt_i32_e32 vcc, s10, v2
	v_mov_b32_e32 v100, 0
	v_mov_b32_e32 v101, 0
	v_cndmask_b32_e32 v8, -1, v26, vcc
	v_cmp_lt_i32_e64 s[0:1], -1, v8
	v_mov_b32_e32 v102, 0
	v_mov_b32_e32 v103, 0
	s_and_saveexec_b64 s[6:7], s[0:1]
	s_cbranch_execz .LBB0_46
	v_lshl_add_u64 v[2:3], v[8:9], 2, s[4:5]
	global_load_dwordx4 v[100:103], v[2:3], off
.LBB0_46:
	s_or_b64 exec, exec, s[6:7]
	v_add_u32_e32 v2, 0x2c00, v26
	v_cndmask_b32_e32 v8, -1, v2, vcc
	v_cmp_lt_i32_e64 s[0:1], -1, v8
	v_mov_b32_e32 v108, 0
	v_mov_b32_e32 v104, 0
	v_mov_b32_e32 v105, 0
	v_mov_b32_e32 v106, 0
	v_mov_b32_e32 v107, 0
	s_and_saveexec_b64 s[6:7], s[0:1]
	s_cbranch_execz .LBB0_48
	v_lshl_add_u64 v[4:5], v[8:9], 2, s[4:5]
	global_load_dwordx4 v[104:107], v[4:5], off
.LBB0_48:
	s_or_b64 exec, exec, s[6:7]
	v_add_u32_e32 v3, 0x5800, v26
	v_cndmask_b32_e32 v8, -1, v3, vcc
	v_cmp_lt_i32_e64 s[0:1], -1, v8
	v_mov_b32_e32 v109, 0
	v_mov_b32_e32 v110, 0
	v_mov_b32_e32 v111, 0
	s_and_saveexec_b64 s[6:7], s[0:1]
	s_cbranch_execz .LBB0_50
	v_lshl_add_u64 v[2:3], v[8:9], 2, s[4:5]
	global_load_dwordx4 v[108:111], v[2:3], off
.LBB0_50:
	s_or_b64 exec, exec, s[6:7]
	v_add_u32_e32 v2, 0x8400, v26
	v_cndmask_b32_e32 v8, -1, v2, vcc
	v_cmp_lt_i32_e32 vcc, -1, v8
	v_mov_b32_e32 v112, 0
	v_mov_b32_e32 v113, 0
	v_mov_b32_e32 v114, 0
	v_mov_b32_e32 v115, 0
	s_and_saveexec_b64 s[0:1], vcc
	s_cbranch_execz .LBB0_43
	v_lshl_add_u64 v[2:3], v[8:9], 2, s[4:5]
	global_load_dwordx4 v[112:115], v[2:3], off
	s_branch .LBB0_43

.LBB0_54:
	s_or_b64 exec, exec, s[0:1]
	s_waitcnt vmcnt(0)
	ds_write2_b32 v18, v100, v101 offset1:1
	ds_write2_b32 v18, v102, v103 offset0:2 offset1:3
	ds_write2_b32 v19, v104, v105 offset1:1
	ds_write2_b32 v20, v106, v107 offset1:1
	ds_write2_b32 v21, v108, v109 offset1:1
	ds_write2_b32 v23, v110, v111 offset1:1
	ds_write2_b32 v24, v112, v113 offset1:1
	ds_write2_b32 v25, v114, v115 offset1:1
	s_waitcnt lgkmcnt(0)
	s_barrier
	ds_read2_b32 v[6:7], v14 offset1:32
	ds_read2_b32 v[28:29], v14 offset0:65 offset1:97
	ds_read2_b32 v[30:31], v14 offset0:130 offset1:162
	ds_read2_b32 v[32:33], v14 offset0:195 offset1:227
	ds_read2_b32 v[34:35], v26 offset0:4 offset1:36
	ds_read2_b32 v[36:37], v26 offset0:69 offset1:101
	ds_read2_b32 v[38:39], v26 offset0:134 offset1:166
	ds_read2_b32 v[40:41], v26 offset0:199 offset1:231
	s_mulk_i32 s24, 0xfe80
	s_add_i32 s0, s11, s24
	s_ashr_i32 s1, s0, 31
	v_lshl_add_u64 v[42:43], s[0:1], 1, v[10:11]
	s_waitcnt lgkmcnt(6)
	v_cvt_pk_bf16_f32 v2, v6, v28
	v_add_u32_e32 v6, s23, v13
	s_waitcnt lgkmcnt(4)
	v_cvt_pk_bf16_f32 v3, v30, v32
	s_waitcnt lgkmcnt(2)
	v_cvt_pk_bf16_f32 v4, v34, v36
	s_waitcnt lgkmcnt(0)
	v_cvt_pk_bf16_f32 v5, v38, v40
	v_mad_i64_i32 v[44:45], s[0:1], v6, s22, v[42:43]
	v_add_u32_e32 v6, 32, v6
	s_add_i32 s10, s10, s33
	s_add_i32 s11, s11, s20
	global_store_dwordx4 v[44:45], v[2:5], off sc1
	s_cmpk_lt_i32 s10, 0x90
	v_add_u32_e32 v15, s9, v15
	v_cvt_pk_bf16_f32 v2, v7, v29
	v_cvt_pk_bf16_f32 v3, v31, v33
	v_cvt_pk_bf16_f32 v4, v35, v37
	v_cvt_pk_bf16_f32 v5, v39, v41
	v_mad_i64_i32 v[6:7], s[0:1], v6, s22, v[42:43]
	global_store_dwordx4 v[6:7], v[2:5], off sc1
	s_barrier
	s_cbranch_scc0 .LBB0_63
.LBB0_55:
	s_mul_hi_i32 s24, s10, 0x2aaaaaab
	s_lshr_b32 s0, s24, 31
	s_add_i32 s24, s24, s0
	s_lshl_b32 s23, s24, 6
	s_add_i32 s0, s23, 0xfffffc00
	s_lshr_b32 s1, s24, 1
	s_lshr_b32 s0, s0, 6
	s_mulk_i32 s1, 0xc0
	v_bitop3_b32 v3, s23, v16, v12 bitop3:0xc8
	s_mulk_i32 s0, 0xc0
	v_add_u32_e32 v3, s1, v3
	s_mul_i32 s1, s24, 0x90000
	v_subrev_u32_e32 v3, s1, v3
	s_sub_i32 s0, s0, s1
	v_or_b32_e32 v2, s23, v12
	v_add_u32_e32 v27, v15, v3
	v_add3_u32 v28, v12, v15, s0
	v_add_u32_e32 v3, 0xffff4000, v27
	v_add_u32_e32 v4, 0xffff4080, v28
	v_cmp_gt_i32_e32 vcc, s21, v2
	v_mov_b32_e32 v100, 0
	v_mov_b32_e32 v103, 0
	v_cndmask_b32_e32 v8, v4, v3, vcc
	v_cmp_lt_i32_e64 s[0:1], -1, v8
	v_mov_b32_e32 v101, 0
	v_mov_b32_e32 v102, 0
	s_and_saveexec_b64 s[6:7], s[0:1]
	s_cbranch_execz .LBB0_57
	v_lshl_add_u64 v[2:3], v[8:9], 2, s[4:5]
	global_load_dwordx4 v[100:103], v[2:3], off
.LBB0_57:
	s_or_b64 exec, exec, s[6:7]
	v_add_u32_e32 v2, 0xffffa000, v27
	v_add_u32_e32 v3, 0xffffa080, v28
	v_cndmask_b32_e32 v8, v3, v2, vcc
	v_cmp_lt_i32_e64 s[0:1], -1, v8
	v_mov_b32_e32 v108, 0
	v_mov_b32_e32 v104, 0
	v_mov_b32_e32 v105, 0
	v_mov_b32_e32 v106, 0
	v_mov_b32_e32 v107, 0
	s_and_saveexec_b64 s[6:7], s[0:1]
	s_cbranch_execz .LBB0_59
	v_lshl_add_u64 v[4:5], v[8:9], 2, s[4:5]
	global_load_dwordx4 v[104:107], v[4:5], off
.LBB0_59:
	s_or_b64 exec, exec, s[6:7]
	v_add_u32_e32 v3, 0x80, v28
	v_cndmask_b32_e32 v8, v3, v27, vcc
	v_cmp_lt_i32_e64 s[0:1], -1, v8
	v_mov_b32_e32 v109, 0
	v_mov_b32_e32 v110, 0
	v_mov_b32_e32 v111, 0
	s_and_saveexec_b64 s[6:7], s[0:1]
	s_cbranch_execz .LBB0_61
	v_lshl_add_u64 v[2:3], v[8:9], 2, s[4:5]
	global_load_dwordx4 v[108:111], v[2:3], off
.LBB0_61:
	s_or_b64 exec, exec, s[6:7]
	v_add_u32_e32 v2, 0x6000, v27
	v_add_u32_e32 v3, 0x6080, v28
	v_cndmask_b32_e32 v8, v3, v2, vcc
	v_cmp_lt_i32_e32 vcc, -1, v8
	v_mov_b32_e32 v112, 0
	v_mov_b32_e32 v113, 0
	v_mov_b32_e32 v114, 0
	v_mov_b32_e32 v115, 0
	s_and_saveexec_b64 s[0:1], vcc
	s_cbranch_execz .LBB0_54
	v_lshl_add_u64 v[2:3], v[8:9], 2, s[4:5]
	global_load_dwordx4 v[112:115], v[2:3], off
	s_branch .LBB0_54

.LBB0_65:
	s_or_b64 exec, exec, s[4:5]
	s_waitcnt vmcnt(0)
	ds_write2_b32 v19, v100, v101 offset1:1
	ds_write2_b32 v19, v102, v103 offset0:2 offset1:3
	ds_write2_b32 v20, v104, v105 offset1:1
	ds_write2_b32 v21, v106, v107 offset1:1
	ds_write2_b32 v23, v108, v109 offset1:1
	ds_write2_b32 v24, v110, v111 offset1:1
	ds_write2_b32 v25, v112, v113 offset1:1
	ds_write2_b32 v26, v114, v115 offset1:1
	s_waitcnt lgkmcnt(0)
	s_barrier
	ds_read2_b32 v[6:7], v16 offset1:32
	ds_read2_b32 v[12:13], v16 offset0:65 offset1:97
	ds_read2_b32 v[28:29], v16 offset0:130 offset1:162
	ds_read2_b32 v[30:31], v16 offset0:195 offset1:227
	ds_read2_b32 v[32:33], v27 offset0:4 offset1:36
	ds_read2_b32 v[34:35], v27 offset0:69 offset1:101
	ds_read2_b32 v[36:37], v27 offset0:134 offset1:166
	ds_read2_b32 v[38:39], v27 offset0:199 offset1:231
	s_lshl_b32 s4, s20, 8
	s_sub_i32 s4, s10, s4
	v_lshl_add_u32 v42, s20, 6, v15
	s_ashr_i32 s5, s4, 31
	v_ashrrev_i32_e32 v43, 31, v42
	v_lshl_add_u64 v[40:41], s[4:5], 1, v[10:11]
	v_lshlrev_b64 v[44:45], 9, v[42:43]
	s_waitcnt lgkmcnt(6)
	v_cvt_pk_bf16_f32 v2, v6, v12
	s_waitcnt lgkmcnt(4)
	v_cvt_pk_bf16_f32 v3, v28, v30
	s_waitcnt lgkmcnt(2)
	v_cvt_pk_bf16_f32 v4, v32, v34
	s_waitcnt lgkmcnt(0)
	v_cvt_pk_bf16_f32 v5, v36, v38
	v_lshl_add_u64 v[44:45], v[40:41], 0, v[44:45]
	v_add_u32_e32 v6, 32, v42
	global_store_dwordx4 v[44:45], v[2:5], off sc1
	s_add_i32 s6, s6, s33
	s_add_i32 s10, s10, s11
	v_cvt_pk_bf16_f32 v2, v7, v13
	v_ashrrev_i32_e32 v7, 31, v6
	v_lshlrev_b64 v[6:7], 9, v[6:7]
	v_cvt_pk_bf16_f32 v3, v29, v31
	v_cvt_pk_bf16_f32 v4, v33, v35
	v_cvt_pk_bf16_f32 v5, v37, v39
	v_lshl_add_u64 v[6:7], v[40:41], 0, v[6:7]
	s_cmpk_lt_i32 s6, 0x80
	v_add_u32_e32 v18, s7, v18
	global_store_dwordx4 v[6:7], v[2:5], off sc1
	s_barrier
	s_cbranch_scc0 .LBB0_74
.LBB0_66:
	s_ashr_i32 s4, s6, 31
	s_lshr_b32 s4, s4, 30
	s_add_i32 s4, s6, s4
	s_ashr_i32 s20, s4, 2
	s_mul_i32 s4, s20, 0xfff80040
	v_add_u32_e32 v8, s4, v18
	v_cmp_lt_i32_e32 vcc, -1, v8
	v_mov_b32_e32 v100, 0
	v_mov_b32_e32 v101, 0
	v_mov_b32_e32 v102, 0
	v_mov_b32_e32 v103, 0
	s_and_saveexec_b64 s[4:5], vcc
	s_cbranch_execz .LBB0_68
	v_lshl_add_u64 v[2:3], v[8:9], 2, s[0:1]
	global_load_dwordx4 v[100:103], v[2:3], off
.LBB0_68:
	s_or_b64 exec, exec, s[4:5]
	v_add_u32_e32 v12, 0x8000, v8
	v_cmp_lt_i32_e32 vcc, -1, v12
	v_mov_b32_e32 v108, 0
	v_mov_b32_e32 v104, 0
	v_mov_b32_e32 v105, 0
	v_mov_b32_e32 v106, 0
	v_mov_b32_e32 v107, 0
	s_and_saveexec_b64 s[4:5], vcc
	s_cbranch_execz .LBB0_70
	v_mov_b32_e32 v13, v9
	v_lshl_add_u64 v[4:5], v[12:13], 2, s[0:1]
	global_load_dwordx4 v[104:107], v[4:5], off
.LBB0_70:
	s_or_b64 exec, exec, s[4:5]
	v_add_u32_e32 v6, 0x10000, v8
	v_cmp_lt_i32_e32 vcc, -1, v6
	v_mov_b32_e32 v109, 0
	v_mov_b32_e32 v110, 0
	v_mov_b32_e32 v111, 0
	s_and_saveexec_b64 s[4:5], vcc
	s_cbranch_execz .LBB0_72
	v_mov_b32_e32 v7, v9
	v_lshl_add_u64 v[2:3], v[6:7], 2, s[0:1]
	global_load_dwordx4 v[108:111], v[2:3], off
.LBB0_72:
	s_or_b64 exec, exec, s[4:5]
	v_add_u32_e32 v8, 0x18000, v8
	v_cmp_lt_i32_e32 vcc, -1, v8
	v_mov_b32_e32 v112, 0
	v_mov_b32_e32 v113, 0
	v_mov_b32_e32 v114, 0
	v_mov_b32_e32 v115, 0
	s_and_saveexec_b64 s[4:5], vcc
	s_cbranch_execz .LBB0_65
	v_lshl_add_u64 v[2:3], v[8:9], 2, s[0:1]
	global_load_dwordx4 v[112:115], v[2:3], off
	s_branch .LBB0_65

.LBB0_76:
	s_or_b64 exec, exec, s[4:5]
	s_waitcnt vmcnt(0)
	ds_write2_b32 v20, v100, v101 offset1:1
	ds_write2_b32 v20, v102, v103 offset0:2 offset1:3
	ds_write2_b32 v21, v104, v105 offset1:1
	ds_write2_b32 v23, v106, v107 offset1:1
	ds_write2_b32 v24, v108, v109 offset1:1
	ds_write2_b32 v25, v110, v111 offset1:1
	ds_write2_b32 v26, v112, v113 offset1:1
	ds_write2_b32 v27, v114, v115 offset1:1
	s_waitcnt lgkmcnt(0)
	s_barrier
	ds_read2_b32 v[6:7], v18 offset1:32
	ds_read2_b32 v[12:13], v18 offset0:65 offset1:97
	ds_read2_b32 v[30:31], v18 offset0:130 offset1:162
	ds_read2_b32 v[32:33], v18 offset0:195 offset1:227
	ds_read2_b32 v[34:35], v28 offset0:4 offset1:36
	ds_read2_b32 v[36:37], v28 offset0:69 offset1:101
	ds_read2_b32 v[38:39], v28 offset0:134 offset1:166
	ds_read2_b32 v[40:41], v28 offset0:199 offset1:231
	s_lshl_b32 s4, s20, 10
	s_sub_i32 s4, s10, s4
	v_lshl_add_u32 v44, s20, 6, v15
	s_ashr_i32 s5, s4, 31
	v_ashrrev_i32_e32 v45, 31, v44
	v_lshl_add_u64 v[42:43], s[4:5], 1, v[10:11]
	v_lshlrev_b64 v[46:47], 11, v[44:45]
	s_waitcnt lgkmcnt(6)
	v_cvt_pk_bf16_f32 v2, v6, v12
	s_waitcnt lgkmcnt(4)
	v_cvt_pk_bf16_f32 v3, v30, v32
	s_waitcnt lgkmcnt(2)
	v_cvt_pk_bf16_f32 v4, v34, v36
	s_waitcnt lgkmcnt(0)
	v_cvt_pk_bf16_f32 v5, v38, v40
	v_lshl_add_u64 v[46:47], v[42:43], 0, v[46:47]
	v_add_u32_e32 v6, 32, v44
	global_store_dwordx4 v[46:47], v[2:5], off sc1
	s_add_i32 s6, s6, s33
	s_add_i32 s10, s10, s11
	v_cvt_pk_bf16_f32 v2, v7, v13
	v_ashrrev_i32_e32 v7, 31, v6
	v_lshlrev_b64 v[6:7], 11, v[6:7]
	v_cvt_pk_bf16_f32 v3, v31, v33
	v_cvt_pk_bf16_f32 v4, v35, v37
	v_cvt_pk_bf16_f32 v5, v39, v41
	v_lshl_add_u64 v[6:7], v[42:43], 0, v[6:7]
	s_cmpk_lt_i32 s6, 0x100
	v_add_u32_e32 v19, s7, v19
	global_store_dwordx4 v[6:7], v[2:5], off sc1
	s_barrier
	s_cbranch_scc0 .LBB0_85
.LBB0_77:
	s_ashr_i32 s4, s6, 31
	s_lshr_b32 s4, s4, 28
	s_add_i32 s4, s6, s4
	s_ashr_i32 s20, s4, 4
	s_mul_i32 s4, s20, 0xfff00040
	v_add_u32_e32 v8, s4, v19
	v_cmp_lt_i32_e32 vcc, -1, v8
	v_mov_b32_e32 v100, 0
	v_mov_b32_e32 v101, 0
	v_mov_b32_e32 v102, 0
	v_mov_b32_e32 v103, 0
	s_and_saveexec_b64 s[4:5], vcc
	s_cbranch_execz .LBB0_79
	v_lshl_add_u64 v[2:3], v[8:9], 2, s[0:1]
	global_load_dwordx4 v[100:103], v[2:3], off
.LBB0_79:
	s_or_b64 exec, exec, s[4:5]
	v_add_u32_e32 v12, 0x4000, v8
	v_cmp_lt_i32_e32 vcc, -1, v12
	v_mov_b32_e32 v108, 0
	v_mov_b32_e32 v104, 0
	v_mov_b32_e32 v105, 0
	v_mov_b32_e32 v106, 0
	v_mov_b32_e32 v107, 0
	s_and_saveexec_b64 s[4:5], vcc
	s_cbranch_execz .LBB0_81
	v_mov_b32_e32 v13, v9
	v_lshl_add_u64 v[4:5], v[12:13], 2, s[0:1]
	global_load_dwordx4 v[104:107], v[4:5], off
.LBB0_81:
	s_or_b64 exec, exec, s[4:5]
	v_add_u32_e32 v6, 0x8000, v8
	v_cmp_lt_i32_e32 vcc, -1, v6
	v_mov_b32_e32 v109, 0
	v_mov_b32_e32 v110, 0
	v_mov_b32_e32 v111, 0
	s_and_saveexec_b64 s[4:5], vcc
	s_cbranch_execz .LBB0_83
	v_mov_b32_e32 v7, v9
	v_lshl_add_u64 v[2:3], v[6:7], 2, s[0:1]
	global_load_dwordx4 v[108:111], v[2:3], off
.LBB0_83:
	s_or_b64 exec, exec, s[4:5]
	v_add_u32_e32 v8, 0xc000, v8
	v_cmp_lt_i32_e32 vcc, -1, v8
	v_mov_b32_e32 v112, 0
	v_mov_b32_e32 v113, 0
	v_mov_b32_e32 v114, 0
	v_mov_b32_e32 v115, 0
	s_and_saveexec_b64 s[4:5], vcc
	s_cbranch_execz .LBB0_76
	v_lshl_add_u64 v[2:3], v[8:9], 2, s[0:1]
	global_load_dwordx4 v[112:115], v[2:3], off
	s_branch .LBB0_76

.LBB0_87:
	s_or_b64 exec, exec, s[4:5]
	s_waitcnt vmcnt(0)
	ds_write2_b32 v20, v100, v101 offset1:1
	ds_write2_b32 v20, v102, v103 offset0:2 offset1:3
	ds_write2_b32 v21, v104, v105 offset1:1
	ds_write2_b32 v23, v106, v107 offset1:1
	ds_write2_b32 v24, v108, v109 offset1:1
	ds_write2_b32 v25, v110, v111 offset1:1
	ds_write2_b32 v26, v112, v113 offset1:1
	ds_write2_b32 v27, v114, v115 offset1:1
	s_waitcnt lgkmcnt(0)
	s_barrier
	ds_read2_b32 v[6:7], v18 offset1:32
	ds_read2_b32 v[12:13], v18 offset0:65 offset1:97
	ds_read2_b32 v[30:31], v18 offset0:130 offset1:162
	ds_read2_b32 v[32:33], v18 offset0:195 offset1:227
	ds_read2_b32 v[34:35], v28 offset0:4 offset1:36
	ds_read2_b32 v[36:37], v28 offset0:69 offset1:101
	ds_read2_b32 v[38:39], v28 offset0:134 offset1:166
	ds_read2_b32 v[40:41], v28 offset0:199 offset1:231
	s_lshl_b32 s4, s20, 10
	s_sub_i32 s4, s10, s4
	v_lshl_add_u32 v44, s20, 6, v15
	s_ashr_i32 s5, s4, 31
	v_ashrrev_i32_e32 v45, 31, v44
	v_lshl_add_u64 v[42:43], s[4:5], 1, v[10:11]
	v_lshlrev_b64 v[46:47], 11, v[44:45]
	s_waitcnt lgkmcnt(6)
	v_cvt_pk_bf16_f32 v2, v6, v12
	s_waitcnt lgkmcnt(4)
	v_cvt_pk_bf16_f32 v3, v30, v32
	s_waitcnt lgkmcnt(2)
	v_cvt_pk_bf16_f32 v4, v34, v36
	s_waitcnt lgkmcnt(0)
	v_cvt_pk_bf16_f32 v5, v38, v40
	v_lshl_add_u64 v[46:47], v[42:43], 0, v[46:47]
	v_add_u32_e32 v6, 32, v44
	global_store_dwordx4 v[46:47], v[2:5], off sc1
	s_add_i32 s6, s6, s33
	s_add_i32 s10, s10, s11
	v_cvt_pk_bf16_f32 v2, v7, v13
	v_ashrrev_i32_e32 v7, 31, v6
	v_lshlrev_b64 v[6:7], 11, v[6:7]
	v_cvt_pk_bf16_f32 v3, v31, v33
	v_cvt_pk_bf16_f32 v4, v35, v37
	v_cvt_pk_bf16_f32 v5, v39, v41
	v_lshl_add_u64 v[6:7], v[42:43], 0, v[6:7]
	s_cmpk_lt_i32 s6, 0x300
	v_add_u32_e32 v19, s7, v19
	global_store_dwordx4 v[6:7], v[2:5], off sc1
	s_barrier
	s_cbranch_scc0 .LBB0_96
.LBB0_88:
	s_ashr_i32 s4, s6, 31
	s_lshr_b32 s4, s4, 28
	s_add_i32 s4, s6, s4
	s_ashr_i32 s20, s4, 4
	s_mul_i32 s4, s20, 0xffd00040
	v_add_u32_e32 v8, s4, v19
	v_cmp_lt_i32_e32 vcc, -1, v8
	v_mov_b32_e32 v100, 0
	v_mov_b32_e32 v101, 0
	v_mov_b32_e32 v102, 0
	v_mov_b32_e32 v103, 0
	s_and_saveexec_b64 s[4:5], vcc
	s_cbranch_execz .LBB0_90
	v_lshl_add_u64 v[2:3], v[8:9], 2, s[0:1]
	global_load_dwordx4 v[100:103], v[2:3], off
.LBB0_90:
	s_or_b64 exec, exec, s[4:5]
	v_add_u32_e32 v12, 0xc000, v8
	v_cmp_lt_i32_e32 vcc, -1, v12
	v_mov_b32_e32 v108, 0
	v_mov_b32_e32 v104, 0
	v_mov_b32_e32 v105, 0
	v_mov_b32_e32 v106, 0
	v_mov_b32_e32 v107, 0
	s_and_saveexec_b64 s[4:5], vcc
	s_cbranch_execz .LBB0_92
	v_mov_b32_e32 v13, v9
	v_lshl_add_u64 v[4:5], v[12:13], 2, s[0:1]
	global_load_dwordx4 v[104:107], v[4:5], off
.LBB0_92:
	s_or_b64 exec, exec, s[4:5]
	v_add_u32_e32 v6, 0x18000, v8
	v_cmp_lt_i32_e32 vcc, -1, v6
	v_mov_b32_e32 v109, 0
	v_mov_b32_e32 v110, 0
	v_mov_b32_e32 v111, 0
	s_and_saveexec_b64 s[4:5], vcc
	s_cbranch_execz .LBB0_94
	v_mov_b32_e32 v7, v9
	v_lshl_add_u64 v[2:3], v[6:7], 2, s[0:1]
	global_load_dwordx4 v[108:111], v[2:3], off
.LBB0_94:
	s_or_b64 exec, exec, s[4:5]
	v_add_u32_e32 v8, 0x24000, v8
	v_cmp_lt_i32_e32 vcc, -1, v8
	v_mov_b32_e32 v112, 0
	v_mov_b32_e32 v113, 0
	v_mov_b32_e32 v114, 0
	v_mov_b32_e32 v115, 0
	s_and_saveexec_b64 s[4:5], vcc
	s_cbranch_execz .LBB0_87
	v_lshl_add_u64 v[2:3], v[8:9], 2, s[0:1]
	global_load_dwordx4 v[112:115], v[2:3], off
	s_branch .LBB0_87

.LBB0_109:
	s_or_b64 exec, exec, s[4:5]
	s_waitcnt vmcnt(0)
	ds_write2_b32 v20, v100, v101 offset1:1
	ds_write2_b32 v20, v102, v103 offset0:2 offset1:3
	ds_write2_b32 v21, v104, v105 offset1:1
	ds_write2_b32 v23, v106, v107 offset1:1
	ds_write2_b32 v24, v108, v109 offset1:1
	ds_write2_b32 v25, v110, v111 offset1:1
	ds_write2_b32 v26, v112, v113 offset1:1
	ds_write2_b32 v27, v114, v115 offset1:1
	s_waitcnt lgkmcnt(0)
	s_barrier
	ds_read2_b32 v[6:7], v18 offset1:32
	ds_read2_b32 v[12:13], v18 offset0:65 offset1:97
	ds_read2_b32 v[30:31], v18 offset0:130 offset1:162
	ds_read2_b32 v[32:33], v18 offset0:195 offset1:227
	ds_read2_b32 v[34:35], v28 offset0:4 offset1:36
	ds_read2_b32 v[36:37], v28 offset0:69 offset1:101
	ds_read2_b32 v[38:39], v28 offset0:134 offset1:166
	ds_read2_b32 v[40:41], v28 offset0:199 offset1:231
	s_lshl_b32 s4, s11, 10
	s_sub_i32 s4, s7, s4
	v_lshl_add_u32 v44, s11, 6, v15
	s_ashr_i32 s5, s4, 31
	v_ashrrev_i32_e32 v45, 31, v44
	v_lshl_add_u64 v[42:43], s[4:5], 1, v[10:11]
	v_lshlrev_b64 v[46:47], 11, v[44:45]
	s_waitcnt lgkmcnt(6)
	v_cvt_pk_bf16_f32 v2, v6, v12
	s_waitcnt lgkmcnt(4)
	v_cvt_pk_bf16_f32 v3, v30, v32
	s_waitcnt lgkmcnt(2)
	v_cvt_pk_bf16_f32 v4, v34, v36
	s_waitcnt lgkmcnt(0)
	v_cvt_pk_bf16_f32 v5, v38, v40
	v_lshl_add_u64 v[46:47], v[42:43], 0, v[46:47]
	v_add_u32_e32 v6, 32, v44
	global_store_dwordx4 v[46:47], v[2:5], off sc1
	s_add_i32 s6, s6, s33
	s_add_i32 s7, s7, s10
	v_cvt_pk_bf16_f32 v2, v7, v13
	v_ashrrev_i32_e32 v7, 31, v6
	v_lshlrev_b64 v[6:7], 11, v[6:7]
	v_cvt_pk_bf16_f32 v3, v31, v33
	v_cvt_pk_bf16_f32 v4, v35, v37
	v_cvt_pk_bf16_f32 v5, v39, v41
	v_lshl_add_u64 v[6:7], v[42:43], 0, v[6:7]
	s_cmpk_lt_i32 s6, 0x180
	v_add_u32_e32 v19, s9, v19
	global_store_dwordx4 v[6:7], v[2:5], off sc1
	s_barrier
	s_cbranch_scc0 .LBB0_118
.LBB0_110:
	s_ashr_i32 s4, s6, 31
	s_lshr_b32 s4, s4, 28
	s_add_i32 s4, s6, s4
	s_ashr_i32 s11, s4, 4
	s_mul_i32 s4, s11, 0xffe80040
	v_add_u32_e32 v8, s4, v19
	v_cmp_lt_i32_e32 vcc, -1, v8
	v_mov_b32_e32 v100, 0
	v_mov_b32_e32 v101, 0
	v_mov_b32_e32 v102, 0
	v_mov_b32_e32 v103, 0
	s_and_saveexec_b64 s[4:5], vcc
	s_cbranch_execz .LBB0_112
	v_lshl_add_u64 v[2:3], v[8:9], 2, s[0:1]
	global_load_dwordx4 v[100:103], v[2:3], off
.LBB0_112:
	s_or_b64 exec, exec, s[4:5]
	v_add_u32_e32 v12, 0x6000, v8
	v_cmp_lt_i32_e32 vcc, -1, v12
	v_mov_b32_e32 v108, 0
	v_mov_b32_e32 v104, 0
	v_mov_b32_e32 v105, 0
	v_mov_b32_e32 v106, 0
	v_mov_b32_e32 v107, 0
	s_and_saveexec_b64 s[4:5], vcc
	s_cbranch_execz .LBB0_114
	v_mov_b32_e32 v13, v9
	v_lshl_add_u64 v[4:5], v[12:13], 2, s[0:1]
	global_load_dwordx4 v[104:107], v[4:5], off
.LBB0_114:
	s_or_b64 exec, exec, s[4:5]
	v_add_u32_e32 v6, 0xc000, v8
	v_cmp_lt_i32_e32 vcc, -1, v6
	v_mov_b32_e32 v109, 0
	v_mov_b32_e32 v110, 0
	v_mov_b32_e32 v111, 0
	s_and_saveexec_b64 s[4:5], vcc
	s_cbranch_execz .LBB0_116
	v_mov_b32_e32 v7, v9
	v_lshl_add_u64 v[2:3], v[6:7], 2, s[0:1]
	global_load_dwordx4 v[108:111], v[2:3], off
.LBB0_116:
	s_or_b64 exec, exec, s[4:5]
	v_add_u32_e32 v8, 0x12000, v8
	v_cmp_lt_i32_e32 vcc, -1, v8
	v_mov_b32_e32 v112, 0
	v_mov_b32_e32 v113, 0
	v_mov_b32_e32 v114, 0
	v_mov_b32_e32 v115, 0
	s_and_saveexec_b64 s[4:5], vcc
	s_cbranch_execz .LBB0_109
	v_lshl_add_u64 v[2:3], v[8:9], 2, s[0:1]
	global_load_dwordx4 v[112:115], v[2:3], off
	s_branch .LBB0_109

.LBB0_120:
	s_or_b64 exec, exec, s[4:5]
	s_waitcnt vmcnt(0)
	ds_write2_b32 v20, v100, v101 offset1:1
	ds_write2_b32 v20, v102, v103 offset0:2 offset1:3
	ds_write2_b32 v21, v104, v105 offset1:1
	ds_write2_b32 v23, v106, v107 offset1:1
	ds_write2_b32 v24, v108, v109 offset1:1
	ds_write2_b32 v25, v110, v111 offset1:1
	ds_write2_b32 v26, v112, v113 offset1:1
	ds_write2_b32 v27, v114, v115 offset1:1
	s_waitcnt lgkmcnt(0)
	s_barrier
	ds_read2_b32 v[6:7], v18 offset1:32
	ds_read2_b32 v[12:13], v18 offset0:65 offset1:97
	ds_read2_b32 v[30:31], v18 offset0:130 offset1:162
	ds_read2_b32 v[32:33], v18 offset0:195 offset1:227
	ds_read2_b32 v[34:35], v28 offset0:4 offset1:36
	ds_read2_b32 v[36:37], v28 offset0:69 offset1:101
	ds_read2_b32 v[38:39], v28 offset0:134 offset1:166
	ds_read2_b32 v[40:41], v28 offset0:199 offset1:231
	s_lshl_b32 s4, s11, 10
	s_sub_i32 s4, s9, s4
	v_lshl_add_u32 v44, s11, 6, v15
	s_ashr_i32 s5, s4, 31
	v_ashrrev_i32_e32 v45, 31, v44
	v_lshl_add_u64 v[42:43], s[4:5], 1, v[10:11]
	v_lshlrev_b64 v[46:47], 11, v[44:45]
	s_waitcnt lgkmcnt(6)
	v_cvt_pk_bf16_f32 v2, v6, v12
	s_waitcnt lgkmcnt(4)
	v_cvt_pk_bf16_f32 v3, v30, v32
	s_waitcnt lgkmcnt(2)
	v_cvt_pk_bf16_f32 v4, v34, v36
	s_waitcnt lgkmcnt(0)
	v_cvt_pk_bf16_f32 v5, v38, v40
	v_lshl_add_u64 v[46:47], v[42:43], 0, v[46:47]
	v_add_u32_e32 v6, 32, v44
	global_store_dwordx4 v[46:47], v[2:5], off sc1
	s_add_i32 s6, s6, s33
	s_add_i32 s9, s9, s10
	v_cvt_pk_bf16_f32 v2, v7, v13
	v_ashrrev_i32_e32 v7, 31, v6
	v_lshlrev_b64 v[6:7], 11, v[6:7]
	v_cvt_pk_bf16_f32 v3, v31, v33
	v_cvt_pk_bf16_f32 v4, v35, v37
	v_cvt_pk_bf16_f32 v5, v39, v41
	v_lshl_add_u64 v[6:7], v[42:43], 0, v[6:7]
	s_cmpk_lt_i32 s6, 0x100
	v_add_u32_e32 v19, s7, v19
	global_store_dwordx4 v[6:7], v[2:5], off sc1
	s_barrier
	s_cbranch_scc0 .LBB0_129
.LBB0_121:
	s_ashr_i32 s4, s6, 31
	s_lshr_b32 s4, s4, 28
	s_add_i32 s4, s6, s4
	s_ashr_i32 s11, s4, 4
	s_mul_i32 s4, s11, 0xfff00040
	v_add_u32_e32 v8, s4, v19
	v_cmp_lt_i32_e32 vcc, -1, v8
	v_mov_b32_e32 v100, 0
	v_mov_b32_e32 v101, 0
	v_mov_b32_e32 v102, 0
	v_mov_b32_e32 v103, 0
	s_and_saveexec_b64 s[4:5], vcc
	s_cbranch_execz .LBB0_123
	v_lshl_add_u64 v[2:3], v[8:9], 2, s[0:1]
	global_load_dwordx4 v[100:103], v[2:3], off

.LBB0_131:
	s_or_b64 exec, exec, s[4:5]
	s_waitcnt vmcnt(0)
	ds_write2_b32 v19, v100, v101 offset1:1
	ds_write2_b32 v19, v102, v103 offset0:2 offset1:3
	ds_write2_b32 v20, v104, v105 offset1:1
	ds_write2_b32 v21, v106, v107 offset1:1
	ds_write2_b32 v23, v108, v109 offset1:1
	ds_write2_b32 v24, v110, v111 offset1:1
	ds_write2_b32 v25, v112, v113 offset1:1
	ds_write2_b32 v26, v114, v115 offset1:1
	s_waitcnt lgkmcnt(0)
	s_barrier
	ds_read2_b32 v[6:7], v18 offset1:32
	ds_read2_b32 v[12:13], v18 offset0:65 offset1:97
	ds_read2_b32 v[28:29], v18 offset0:130 offset1:162
	ds_read2_b32 v[30:31], v18 offset0:195 offset1:227
	ds_read2_b32 v[32:33], v27 offset0:4 offset1:36
	ds_read2_b32 v[34:35], v27 offset0:69 offset1:101
	ds_read2_b32 v[36:37], v27 offset0:134 offset1:166
	ds_read2_b32 v[38:39], v27 offset0:199 offset1:231
	s_lshl_b32 s4, s11, 10
	s_sub_i32 s4, s9, s4
	v_lshl_add_u32 v42, s11, 6, v15
	s_ashr_i32 s5, s4, 31
	v_ashrrev_i32_e32 v43, 31, v42
	v_lshl_add_u64 v[40:41], s[4:5], 1, v[10:11]
	v_lshlrev_b64 v[44:45], 11, v[42:43]
	s_waitcnt lgkmcnt(6)
	v_cvt_pk_bf16_f32 v2, v6, v12
	s_waitcnt lgkmcnt(4)
	v_cvt_pk_bf16_f32 v3, v28, v30
	s_waitcnt lgkmcnt(2)
	v_cvt_pk_bf16_f32 v4, v32, v34
	s_waitcnt lgkmcnt(0)
	v_cvt_pk_bf16_f32 v5, v36, v38
	v_lshl_add_u64 v[44:45], v[40:41], 0, v[44:45]
	v_add_u32_e32 v6, 32, v42
	global_store_dwordx4 v[44:45], v[2:5], off sc1
	s_add_i32 s6, s6, s33
	s_add_i32 s9, s9, s10
	v_cvt_pk_bf16_f32 v2, v7, v13
	v_ashrrev_i32_e32 v7, 31, v6
	v_lshlrev_b64 v[6:7], 11, v[6:7]
	v_cvt_pk_bf16_f32 v3, v29, v31
	v_cvt_pk_bf16_f32 v4, v33, v35
	v_cvt_pk_bf16_f32 v5, v37, v39
	v_lshl_add_u64 v[6:7], v[40:41], 0, v[6:7]
	s_cmpk_lt_i32 s6, 0x200
	v_add_u32_e32 v14, s7, v14
	global_store_dwordx4 v[6:7], v[2:5], off sc1
	s_barrier
	s_cbranch_scc0 .LBB0_140
.LBB0_132:
	s_ashr_i32 s4, s6, 31
	s_lshr_b32 s4, s4, 28
	s_add_i32 s4, s6, s4
	s_ashr_i32 s11, s4, 4
	s_mul_i32 s4, s11, 0xffe00040
	v_add_u32_e32 v8, s4, v14
	v_cmp_lt_i32_e32 vcc, -1, v8
	v_mov_b32_e32 v100, 0
	v_mov_b32_e32 v101, 0
	v_mov_b32_e32 v102, 0
	v_mov_b32_e32 v103, 0
	s_and_saveexec_b64 s[4:5], vcc
	s_cbranch_execz .LBB0_134
	v_lshl_add_u64 v[2:3], v[8:9], 2, s[0:1]
	global_load_dwordx4 v[100:103], v[2:3], off

.LBB0_155:
	s_or_b64 exec, exec, s[4:5]
	v_add_u32_e32 v6, 0x30c0, v23
	s_waitcnt vmcnt(0)
	ds_write2_b32 v23, v100, v101 offset1:1
	ds_write2_b32 v23, v102, v103 offset0:2 offset1:3
	ds_write2_b32 v24, v104, v105 offset1:1
	ds_write2_b32 v26, v106, v107 offset1:1
	ds_write2_b32 v27, v108, v109 offset1:1
	ds_write2_b32 v28, v110, v111 offset1:1
	ds_write2_b32 v6, v112, v113 offset1:1
	v_add_u32_e32 v2, 0x30c8, v23
	ds_write2_b32 v2, v114, v115 offset1:1
	v_add_u32_e32 v2, 0x400, v20
	s_waitcnt lgkmcnt(0)
	s_barrier
	ds_read2_b32 v[6:7], v20 offset1:32
	ds_read2_b32 v[14:15], v20 offset0:65 offset1:97
	ds_read2_b32 v[30:31], v20 offset0:130 offset1:162
	ds_read2_b32 v[32:33], v20 offset0:195 offset1:227
	ds_read2_b32 v[34:35], v2 offset0:4 offset1:36
	ds_read2_b32 v[36:37], v2 offset0:69 offset1:101
	ds_read2_b32 v[38:39], v2 offset0:134 offset1:166
	ds_read2_b32 v[40:41], v2 offset0:199 offset1:231
	s_lshl_b32 s4, s11, 10
	s_lshl_b32 s11, s11, 6
	s_sub_i32 s4, s10, s4
	v_add_u32_e32 v44, s11, v18
	s_ashr_i32 s5, s4, 31
	v_ashrrev_i32_e32 v45, 31, v44
	v_lshl_add_u64 v[42:43], s[4:5], 1, v[12:13]
	v_lshlrev_b64 v[44:45], 11, v[44:45]
	s_waitcnt lgkmcnt(6)
	v_cvt_pk_bf16_f32 v2, v6, v14
	s_waitcnt lgkmcnt(4)
	v_cvt_pk_bf16_f32 v3, v30, v32
	s_waitcnt lgkmcnt(2)
	v_cvt_pk_bf16_f32 v4, v34, v36
	s_waitcnt lgkmcnt(0)
	v_cvt_pk_bf16_f32 v5, v38, v40
	v_lshl_add_u64 v[44:45], v[42:43], 0, v[44:45]
	v_add_u32_e32 v6, s11, v19
	global_store_dwordx4 v[44:45], v[2:5], off sc1
	s_add_i32 s6, s6, s33
	s_add_i32 s10, s10, s9
	v_cvt_pk_bf16_f32 v2, v7, v15
	v_ashrrev_i32_e32 v7, 31, v6
	v_lshlrev_b64 v[6:7], 11, v[6:7]
	v_cvt_pk_bf16_f32 v3, v31, v33
	v_cvt_pk_bf16_f32 v4, v35, v37
	v_cvt_pk_bf16_f32 v5, v39, v41
	v_lshl_add_u64 v[6:7], v[42:43], 0, v[6:7]
	s_cmpk_lt_i32 s6, 0x100
	v_add_u32_e32 v22, s7, v22
	global_store_dwordx4 v[6:7], v[2:5], off sc1
	s_barrier
	s_cbranch_scc0 .LBB0_164
.LBB0_156:
	s_ashr_i32 s4, s6, 31
	s_lshr_b32 s4, s4, 28
	s_add_i32 s4, s6, s4
	s_ashr_i32 s11, s4, 4
	s_mul_i32 s4, s11, 0xfff00040
	v_add_u32_e32 v10, s4, v22
	v_cmp_lt_i32_e32 vcc, -1, v10
	v_mov_b32_e32 v100, 0
	v_mov_b32_e32 v101, 0
	v_mov_b32_e32 v102, 0
	v_mov_b32_e32 v103, 0
	s_and_saveexec_b64 s[4:5], vcc
	s_cbranch_execz .LBB0_158
	v_lshl_add_u64 v[2:3], v[10:11], 2, s[0:1]
	global_load_dwordx4 v[100:103], v[2:3], off
.LBB0_158:
	s_or_b64 exec, exec, s[4:5]
	v_add_u32_e32 v14, 0x4000, v10
	v_cmp_lt_i32_e32 vcc, -1, v14
	v_mov_b32_e32 v108, 0
	v_mov_b32_e32 v104, 0
	v_mov_b32_e32 v105, 0
	v_mov_b32_e32 v106, 0
	v_mov_b32_e32 v107, 0
	s_and_saveexec_b64 s[4:5], vcc
	s_cbranch_execz .LBB0_160
	v_mov_b32_e32 v15, v11
	v_lshl_add_u64 v[4:5], v[14:15], 2, s[0:1]
	global_load_dwordx4 v[104:107], v[4:5], off
.LBB0_160:
	s_or_b64 exec, exec, s[4:5]
	v_add_u32_e32 v6, 0x8000, v10
	v_cmp_lt_i32_e32 vcc, -1, v6
	v_mov_b32_e32 v109, 0
	v_mov_b32_e32 v110, 0
	v_mov_b32_e32 v111, 0
	s_and_saveexec_b64 s[4:5], vcc
	s_cbranch_execz .LBB0_162
	v_mov_b32_e32 v7, v11
	v_lshl_add_u64 v[2:3], v[6:7], 2, s[0:1]
	global_load_dwordx4 v[108:111], v[2:3], off
.LBB0_162:
	s_or_b64 exec, exec, s[4:5]
	v_add_u32_e32 v10, 0xc000, v10
	v_cmp_lt_i32_e32 vcc, -1, v10
	v_mov_b32_e32 v112, 0
	v_mov_b32_e32 v113, 0
	v_mov_b32_e32 v114, 0
	v_mov_b32_e32 v115, 0
	s_and_saveexec_b64 s[4:5], vcc
	s_cbranch_execz .LBB0_155
	v_lshl_add_u64 v[2:3], v[10:11], 2, s[0:1]
	global_load_dwordx4 v[112:115], v[2:3], off
	s_branch .LBB0_155

.LBB0_169:
	s_or_b64 exec, exec, s[6:7]
	s_waitcnt vmcnt(0)
	ds_write2_b32 v25, v100, v101 offset1:1
	ds_write2_b32 v25, v102, v103 offset0:2 offset1:3
	ds_write2_b32 v26, v104, v105 offset1:1
	ds_write2_b32 v27, v106, v107 offset1:1
	ds_write2_b32 v28, v108, v109 offset1:1
	ds_write2_b32 v29, v110, v111 offset1:1
	ds_write2_b32 v30, v112, v113 offset1:1
	ds_write2_b32 v31, v114, v115 offset1:1
	s_waitcnt lgkmcnt(0)
	s_barrier
	ds_read2_b32 v[2:3], v21 offset1:65
	ds_read2_b32 v[4:5], v21 offset0:130 offset1:195
	v_add_u32_e32 v12, 0x400, v21
	ds_read2_b32 v[6:7], v12 offset0:4 offset1:69
	ds_read2_b32 v[16:17], v12 offset0:134 offset1:199
	s_lshl_b32 s6, s25, 10
	s_lshl_b32 s25, s25, 6
	s_sub_i32 s6, s24, s6
	s_waitcnt lgkmcnt(3)
	v_cvt_pk_bf16_f32 v2, v2, v3
	s_waitcnt lgkmcnt(2)
	v_cvt_pk_bf16_f32 v3, v4, v5
	s_waitcnt lgkmcnt(1)
	v_cvt_pk_bf16_f32 v4, v6, v7
	v_add_u32_e32 v6, s25, v18
	s_ashr_i32 s7, s6, 31
	v_ashrrev_i32_e32 v7, 31, v6
	v_add_u32_e32 v12, 0x400, v22
	v_lshl_add_u64 v[34:35], s[6:7], 1, v[14:15]
	s_waitcnt lgkmcnt(0)
	v_cvt_pk_bf16_f32 v5, v16, v17
	v_lshlrev_b64 v[6:7], 11, v[6:7]
	ds_read2_b32 v[16:17], v22 offset1:65
	ds_read2_b32 v[36:37], v22 offset0:130 offset1:195
	ds_read2_b32 v[38:39], v12 offset0:4 offset1:69
	ds_read2_b32 v[40:41], v12 offset0:134 offset1:199
	v_lshl_add_u64 v[6:7], v[34:35], 0, v[6:7]
	global_store_dwordx4 v[6:7], v[2:5], off sc1
	v_add_u32_e32 v6, s25, v19
	v_ashrrev_i32_e32 v7, 31, v6
	v_lshlrev_b64 v[6:7], 11, v[6:7]
	s_add_i32 s23, s23, s33
	s_add_i32 s24, s24, s9
	s_waitcnt lgkmcnt(3)
	v_cvt_pk_bf16_f32 v2, v16, v17
	s_waitcnt lgkmcnt(2)
	v_cvt_pk_bf16_f32 v3, v36, v37
	s_waitcnt lgkmcnt(1)
	v_cvt_pk_bf16_f32 v4, v38, v39
	s_waitcnt lgkmcnt(0)
	v_cvt_pk_bf16_f32 v5, v40, v41
	v_lshl_add_u64 v[6:7], v[34:35], 0, v[6:7]
	s_cmpk_lt_i32 s23, 0x580
	v_add_u32_e32 v33, s20, v33
	global_store_dwordx4 v[6:7], v[2:5], off sc1
	s_barrier
	s_cbranch_scc0 .LBB0_178
.LBB0_170:
	s_ashr_i32 s6, s23, 31
	s_lshr_b32 s6, s6, 28
	s_add_i32 s6, s23, s6
	s_ashr_i32 s25, s6, 4
	s_bfe_i32 s6, s25, 0x10000
	s_lshl_b32 s7, s25, 5
	s_and_b32 s6, s6, 0xb00
	s_andn2_b32 s7, s7, 63
	s_add_i32 s6, s6, s7
	s_mul_i32 s7, s25, 0x580000
	s_sub_i32 s6, s6, s7
	v_add_u32_e32 v12, s6, v33
	v_cmp_lt_i32_e32 vcc, -1, v12
	v_mov_b32_e32 v104, 0
	v_mov_b32_e32 v100, 0
	v_mov_b32_e32 v101, 0
	v_mov_b32_e32 v102, 0
	v_mov_b32_e32 v103, 0
	s_and_saveexec_b64 s[6:7], vcc
	s_cbranch_execz .LBB0_172
	v_lshl_add_u64 v[4:5], v[12:13], 2, s[4:5]
	global_load_dwordx4 v[100:103], v[4:5], off
.LBB0_172:
	s_or_b64 exec, exec, s[6:7]
	v_add_u32_e32 v6, 0x16000, v12
	v_cmp_lt_i32_e32 vcc, -1, v6
	v_mov_b32_e32 v105, 0
	v_mov_b32_e32 v106, 0
	v_mov_b32_e32 v107, 0
	s_and_saveexec_b64 s[6:7], vcc
	s_cbranch_execz .LBB0_174
	v_mov_b32_e32 v7, v13
	v_lshl_add_u64 v[2:3], v[6:7], 2, s[4:5]
	global_load_dwordx4 v[104:107], v[2:3], off
.LBB0_174:
	s_or_b64 exec, exec, s[6:7]
	v_add_u32_e32 v16, 0x2c000, v12
	v_cmp_lt_i32_e32 vcc, -1, v16
	v_mov_b32_e32 v112, 0
	v_mov_b32_e32 v108, 0
	v_mov_b32_e32 v109, 0
	v_mov_b32_e32 v110, 0
	v_mov_b32_e32 v111, 0
	s_and_saveexec_b64 s[6:7], vcc
	s_cbranch_execz .LBB0_176
	v_mov_b32_e32 v17, v13
	v_lshl_add_u64 v[4:5], v[16:17], 2, s[4:5]
	global_load_dwordx4 v[108:111], v[4:5], off
.LBB0_176:
	s_or_b64 exec, exec, s[6:7]
	v_add_u32_e32 v12, 0x42000, v12
	v_cmp_lt_i32_e32 vcc, -1, v12
	v_mov_b32_e32 v113, 0
	v_mov_b32_e32 v114, 0
	v_mov_b32_e32 v115, 0
	s_and_saveexec_b64 s[6:7], vcc
	s_cbranch_execz .LBB0_169
	v_lshl_add_u64 v[2:3], v[12:13], 2, s[4:5]
	global_load_dwordx4 v[112:115], v[2:3], off
	s_branch .LBB0_169

.LBB0_180:
	s_or_b64 exec, exec, s[4:5]
	v_add_u32_e32 v12, 0x400, v21
	s_waitcnt vmcnt(0)
	ds_write2_b32 v25, v100, v101 offset1:1
	ds_write2_b32 v25, v102, v103 offset0:2 offset1:3
	ds_write2_b32 v26, v104, v105 offset1:1
	ds_write2_b32 v27, v106, v107 offset1:1
	ds_write2_b32 v28, v108, v109 offset1:1
	ds_write2_b32 v29, v110, v111 offset1:1
	ds_write2_b32 v30, v112, v113 offset1:1
	ds_write2_b32 v31, v114, v115 offset1:1
	s_waitcnt lgkmcnt(0)
	s_barrier
	ds_read2_b32 v[2:3], v21 offset1:65
	ds_read2_b32 v[4:5], v21 offset0:130 offset1:195
	ds_read2_b32 v[6:7], v12 offset0:4 offset1:69
	ds_read2_b32 v[16:17], v12 offset0:134 offset1:199
	s_mul_i32 s4, s23, 0xfffff500
	v_add_u32_e32 v12, 0x400, v22
	s_add_i32 s4, s7, s4
	s_waitcnt lgkmcnt(3)
	v_cvt_pk_bf16_f32 v2, v2, v3
	s_waitcnt lgkmcnt(2)
	v_cvt_pk_bf16_f32 v3, v4, v5
	s_waitcnt lgkmcnt(0)
	v_cvt_pk_bf16_f32 v5, v16, v17
	ds_read2_b32 v[16:17], v22 offset1:65
	ds_read2_b32 v[36:37], v22 offset0:130 offset1:195
	ds_read2_b32 v[38:39], v12 offset0:4 offset1:69
	ds_read2_b32 v[40:41], v12 offset0:134 offset1:199
	s_lshl_b32 s23, s23, 6
	s_ashr_i32 s5, s4, 31
	v_lshl_add_u64 v[34:35], s[4:5], 1, v[14:15]
	v_cvt_pk_bf16_f32 v4, v6, v7
	v_add_u32_e32 v6, s23, v18
	v_mad_i64_i32 v[6:7], s[4:5], v6, s11, v[34:35]
	global_store_dwordx4 v[6:7], v[2:5], off sc1
	v_add_u32_e32 v6, s23, v19
	s_add_i32 s6, s6, s33
	s_add_i32 s7, s7, s9
	s_waitcnt lgkmcnt(3)
	v_cvt_pk_bf16_f32 v2, v16, v17
	s_waitcnt lgkmcnt(2)
	v_cvt_pk_bf16_f32 v3, v36, v37
	s_waitcnt lgkmcnt(1)
	v_cvt_pk_bf16_f32 v4, v38, v39
	s_waitcnt lgkmcnt(0)
	v_cvt_pk_bf16_f32 v5, v40, v41
	v_mad_i64_i32 v[6:7], s[4:5], v6, s11, v[34:35]
	s_cmpk_lt_i32 s6, 0x2c0
	v_add_u32_e32 v33, v33, v20
	global_store_dwordx4 v[6:7], v[2:5], off sc1
	s_barrier
	s_cbranch_scc0 .LBB0_166
.LBB0_181:
	s_mul_hi_i32 s4, s6, 0x2e8ba2e9
	s_lshr_b32 s5, s4, 31
	s_ashr_i32 s23, s4, 3
	s_add_i32 s23, s23, s5
	s_mul_i32 s4, s23, 0xffd40040
	v_add_u32_e32 v12, s4, v33
	v_cmp_lt_i32_e32 vcc, -1, v12
	v_mov_b32_e32 v104, 0
	v_mov_b32_e32 v100, 0
	v_mov_b32_e32 v101, 0
	v_mov_b32_e32 v102, 0
	v_mov_b32_e32 v103, 0
	s_and_saveexec_b64 s[4:5], vcc
	s_cbranch_execz .LBB0_183
	v_lshl_add_u64 v[4:5], v[12:13], 2, s[0:1]
	global_load_dwordx4 v[100:103], v[4:5], off
.LBB0_183:
	s_or_b64 exec, exec, s[4:5]
	v_add_u32_e32 v6, 0x4000, v12
	v_cmp_lt_i32_e32 vcc, -1, v6
	v_mov_b32_e32 v105, 0
	v_mov_b32_e32 v106, 0
	v_mov_b32_e32 v107, 0
	s_and_saveexec_b64 s[4:5], vcc
	s_cbranch_execz .LBB0_185
	v_mov_b32_e32 v7, v13
	v_lshl_add_u64 v[2:3], v[6:7], 2, s[0:1]
	global_load_dwordx4 v[104:107], v[2:3], off
.LBB0_185:
	s_or_b64 exec, exec, s[4:5]
	v_add_u32_e32 v16, 0x8000, v12
	v_cmp_lt_i32_e32 vcc, -1, v16
	v_mov_b32_e32 v112, 0
	v_mov_b32_e32 v108, 0
	v_mov_b32_e32 v109, 0
	v_mov_b32_e32 v110, 0
	v_mov_b32_e32 v111, 0
	s_and_saveexec_b64 s[4:5], vcc
	s_cbranch_execz .LBB0_187
	v_mov_b32_e32 v17, v13
	v_lshl_add_u64 v[4:5], v[16:17], 2, s[0:1]
	global_load_dwordx4 v[108:111], v[4:5], off
.LBB0_187:
	s_or_b64 exec, exec, s[4:5]
	v_add_u32_e32 v12, 0xc000, v12
	v_cmp_lt_i32_e32 vcc, -1, v12
	v_mov_b32_e32 v113, 0
	v_mov_b32_e32 v114, 0
	v_mov_b32_e32 v115, 0
	s_and_saveexec_b64 s[4:5], vcc
	s_cbranch_execz .LBB0_180
	v_lshl_add_u64 v[2:3], v[12:13], 2, s[0:1]
	global_load_dwordx4 v[112:115], v[2:3], off
	s_branch .LBB0_180
